# remove compiler-inserted false-dependency lgkmcnt(0) between B and A fragment reads in the non-TQ GEMM K-loops (6 sites)
# baseline (speedup 1.0000x reference)
.LBB0_447:
	v_add_u32_e32 v0, s23, v225
	ds_read_b128 v[148:151], v0
	ds_read_b128 v[152:155], v0 offset:1024
	ds_read_b128 v[156:159], v0 offset:2048
	ds_read_b128 v[160:163], v0 offset:3072
	v_add_u32_e32 v0, s50, v225
	ds_read_b128 v[132:135], v0
	ds_read_b128 v[136:139], v0 offset:1024
	ds_read_b128 v[140:143], v0 offset:2048
	ds_read_b128 v[144:147], v0 offset:3072
	v_lshl_add_u64 v[2:3], v[216:217], 0, s[28:29]
	s_add_i32 m0, s53, 0xc000
	ds_read_b128 v[176:179], v241
	ds_read_b128 v[192:195], v241 offset:1024
	ds_read_b128 v[172:175], v241 offset:2048
	ds_read_b128 v[188:191], v241 offset:3072
	ds_read_b128 v[168:171], v241 offset:4096
	ds_read_b128 v[184:187], v241 offset:5120
	ds_read_b128 v[164:167], v241 offset:6144
	ds_read_b128 v[180:183], v241 offset:7168
	global_load_lds_dwordx4 v[2:3], off
	v_lshl_add_u64 v[2:3], v[214:215], 0, s[28:29]
	s_add_i32 m0, s53, 0xe000
	s_nop 0
	global_load_lds_dwordx4 v[2:3], off
	s_waitcnt vmcnt(8)
	s_waitcnt lgkmcnt(0)
	s_barrier
	s_setprio 1
	s_waitcnt lgkmcnt(0)
	v_mfma_f32_16x16x32_bf16 v[128:131], v[148:151], v[176:179], v[128:131]
	v_mfma_f32_16x16x32_bf16 v[120:123], v[156:159], v[176:179], v[120:123]
	v_mfma_f32_16x16x32_bf16 v[112:115], v[148:151], v[172:175], v[112:115]
	v_mfma_f32_16x16x32_bf16 v[104:107], v[156:159], v[172:175], v[104:107]
	v_mfma_f32_16x16x32_bf16 v[96:99], v[148:151], v[168:171], v[96:99]
	v_mfma_f32_16x16x32_bf16 v[88:91], v[156:159], v[168:171], v[88:91]
	v_mfma_f32_16x16x32_bf16 v[80:83], v[148:151], v[164:167], v[80:83]
	v_mfma_f32_16x16x32_bf16 v[72:75], v[156:159], v[164:167], v[72:75]
	v_mfma_f32_16x16x32_bf16 v[128:131], v[152:155], v[192:195], v[128:131]
	v_mfma_f32_16x16x32_bf16 v[120:123], v[160:163], v[192:195], v[120:123]
	v_mfma_f32_16x16x32_bf16 v[112:115], v[152:155], v[188:191], v[112:115]
	v_mfma_f32_16x16x32_bf16 v[104:107], v[160:163], v[188:191], v[104:107]
	v_mfma_f32_16x16x32_bf16 v[96:99], v[152:155], v[184:187], v[96:99]
	v_mfma_f32_16x16x32_bf16 v[88:91], v[160:163], v[184:187], v[88:91]
	v_mfma_f32_16x16x32_bf16 v[80:83], v[152:155], v[180:183], v[80:83]
	v_mfma_f32_16x16x32_bf16 v[72:75], v[160:163], v[180:183], v[72:75]
	s_setprio 0
	s_setprio 1
	v_mfma_f32_16x16x32_bf16 v[124:127], v[132:135], v[176:179], v[124:127]
	v_mfma_f32_16x16x32_bf16 v[116:119], v[140:143], v[176:179], v[116:119]
	v_mfma_f32_16x16x32_bf16 v[108:111], v[132:135], v[172:175], v[108:111]
	v_mfma_f32_16x16x32_bf16 v[100:103], v[140:143], v[172:175], v[100:103]
	v_mfma_f32_16x16x32_bf16 v[92:95], v[132:135], v[168:171], v[92:95]
	v_mfma_f32_16x16x32_bf16 v[84:87], v[140:143], v[168:171], v[84:87]
	v_mfma_f32_16x16x32_bf16 v[76:79], v[132:135], v[164:167], v[76:79]
	v_mfma_f32_16x16x32_bf16 v[68:71], v[140:143], v[164:167], v[68:71]
	v_mfma_f32_16x16x32_bf16 v[124:127], v[136:139], v[192:195], v[124:127]
	v_mfma_f32_16x16x32_bf16 v[116:119], v[144:147], v[192:195], v[116:119]
	v_mfma_f32_16x16x32_bf16 v[108:111], v[136:139], v[188:191], v[108:111]
	v_mfma_f32_16x16x32_bf16 v[100:103], v[144:147], v[188:191], v[100:103]
	v_mfma_f32_16x16x32_bf16 v[92:95], v[136:139], v[184:187], v[92:95]
	v_mfma_f32_16x16x32_bf16 v[84:87], v[144:147], v[184:187], v[84:87]
	v_mfma_f32_16x16x32_bf16 v[76:79], v[136:139], v[180:183], v[76:79]
	v_mfma_f32_16x16x32_bf16 v[68:71], v[144:147], v[180:183], v[68:71]
	s_setprio 0
	s_barrier
	v_cndmask_b32_e64 v0, 0, 1, s[30:31]
	v_cmp_ne_u32_e64 s[6:7], 1, v0
	s_andn2_b64 vcc, exec, s[30:31]
	s_cbranch_vccnz .LBB0_449
	ds_read_b128 v[176:179], v241 offset:16384
	ds_read_b128 v[192:195], v241 offset:17408
	ds_read_b128 v[172:175], v241 offset:18432
	ds_read_b128 v[188:191], v241 offset:19456
	ds_read_b128 v[168:171], v241 offset:20480
	ds_read_b128 v[184:187], v241 offset:21504
	ds_read_b128 v[164:167], v241 offset:22528
	ds_read_b128 v[180:183], v241 offset:23552

.LBB0_451:
	s_barrier
	v_add_u32_e32 v0, s57, v225
	ds_read_b128 v[148:151], v0
	ds_read_b128 v[152:155], v0 offset:1024
	ds_read_b128 v[156:159], v0 offset:2048
	ds_read_b128 v[160:163], v0 offset:3072
	v_add_u32_e32 v0, s66, v225
	ds_read_b128 v[132:135], v0
	ds_read_b128 v[136:139], v0 offset:1024
	ds_read_b128 v[140:143], v0 offset:2048
	ds_read_b128 v[144:147], v0 offset:3072
	s_and_b64 s[38:39], s[16:17], s[38:39]
	s_and_b64 s[38:39], s[38:39], exec
	s_cselect_b32 s39, s74, s26
	s_cselect_b32 s38, 0, s27
	s_add_u32 s36, s36, s39
	s_addc_u32 s37, s37, s38
	s_mov_b32 m0, s55
	v_lshl_add_u64 v[242:243], s[36:37], 0, v[202:203]
	ds_read_b128 v[176:179], v241 offset:32768
	ds_read_b128 v[192:195], v241 offset:33792
	ds_read_b128 v[172:175], v241 offset:34816
	ds_read_b128 v[188:191], v241 offset:35840
	ds_read_b128 v[168:171], v241 offset:36864
	ds_read_b128 v[184:187], v241 offset:37888
	ds_read_b128 v[164:167], v241 offset:38912
	ds_read_b128 v[180:183], v241 offset:39936
	global_load_lds_dwordx4 v[242:243], off
	v_lshl_add_u64 v[242:243], s[36:37], 0, v[206:207]
	s_mov_b32 m0, s56
	s_nop 0
	global_load_lds_dwordx4 v[242:243], off
	s_waitcnt vmcnt(8)
	s_waitcnt lgkmcnt(0)
	s_barrier
	s_setprio 1
	s_waitcnt lgkmcnt(0)
	v_mfma_f32_16x16x32_bf16 v[128:131], v[148:151], v[176:179], v[128:131]
	v_mfma_f32_16x16x32_bf16 v[120:123], v[156:159], v[176:179], v[120:123]
	v_mfma_f32_16x16x32_bf16 v[112:115], v[148:151], v[172:175], v[112:115]
	v_mfma_f32_16x16x32_bf16 v[104:107], v[156:159], v[172:175], v[104:107]
	v_mfma_f32_16x16x32_bf16 v[96:99], v[148:151], v[168:171], v[96:99]
	v_mfma_f32_16x16x32_bf16 v[88:91], v[156:159], v[168:171], v[88:91]
	v_mfma_f32_16x16x32_bf16 v[80:83], v[148:151], v[164:167], v[80:83]
	v_mfma_f32_16x16x32_bf16 v[72:75], v[156:159], v[164:167], v[72:75]
	v_mfma_f32_16x16x32_bf16 v[128:131], v[152:155], v[192:195], v[128:131]
	v_mfma_f32_16x16x32_bf16 v[120:123], v[160:163], v[192:195], v[120:123]
	v_mfma_f32_16x16x32_bf16 v[112:115], v[152:155], v[188:191], v[112:115]
	v_mfma_f32_16x16x32_bf16 v[104:107], v[160:163], v[188:191], v[104:107]
	v_mfma_f32_16x16x32_bf16 v[96:99], v[152:155], v[184:187], v[96:99]
	v_mfma_f32_16x16x32_bf16 v[88:91], v[160:163], v[184:187], v[88:91]
	v_mfma_f32_16x16x32_bf16 v[80:83], v[152:155], v[180:183], v[80:83]
	v_mfma_f32_16x16x32_bf16 v[72:75], v[160:163], v[180:183], v[72:75]
	s_setprio 0
	s_setprio 1
	v_mfma_f32_16x16x32_bf16 v[124:127], v[132:135], v[176:179], v[124:127]
	v_mfma_f32_16x16x32_bf16 v[116:119], v[140:143], v[176:179], v[116:119]
	v_mfma_f32_16x16x32_bf16 v[108:111], v[132:135], v[172:175], v[108:111]
	v_mfma_f32_16x16x32_bf16 v[100:103], v[140:143], v[172:175], v[100:103]
	v_mfma_f32_16x16x32_bf16 v[92:95], v[132:135], v[168:171], v[92:95]
	v_mfma_f32_16x16x32_bf16 v[84:87], v[140:143], v[168:171], v[84:87]
	v_mfma_f32_16x16x32_bf16 v[76:79], v[132:135], v[164:167], v[76:79]
	v_mfma_f32_16x16x32_bf16 v[68:71], v[140:143], v[164:167], v[68:71]
	v_mfma_f32_16x16x32_bf16 v[124:127], v[136:139], v[192:195], v[124:127]
	v_mfma_f32_16x16x32_bf16 v[116:119], v[144:147], v[192:195], v[116:119]
	v_mfma_f32_16x16x32_bf16 v[108:111], v[136:139], v[188:191], v[108:111]
	v_mfma_f32_16x16x32_bf16 v[100:103], v[144:147], v[188:191], v[100:103]
	v_mfma_f32_16x16x32_bf16 v[92:95], v[136:139], v[184:187], v[92:95]
	v_mfma_f32_16x16x32_bf16 v[84:87], v[144:147], v[184:187], v[84:87]
	v_mfma_f32_16x16x32_bf16 v[76:79], v[136:139], v[180:183], v[76:79]
	v_mfma_f32_16x16x32_bf16 v[68:71], v[144:147], v[180:183], v[68:71]
	s_setprio 0
	s_barrier
	s_and_b64 vcc, exec, s[6:7]
	s_mov_b64 s[88:89], s[86:87]
	s_cbranch_vccnz .LBB0_453
	ds_read_b128 v[176:179], v241 offset:49152
	ds_read_b128 v[192:195], v241 offset:50176
	ds_read_b128 v[172:175], v241 offset:51200
	ds_read_b128 v[188:191], v241 offset:52224
	ds_read_b128 v[168:171], v241 offset:53248
	ds_read_b128 v[184:187], v241 offset:54272
	ds_read_b128 v[164:167], v241 offset:55296
	ds_read_b128 v[180:183], v241 offset:56320

.LBB0_773:
	v_add_u32_e32 v0, s15, v241
	ds_read_b128 v[148:151], v0
	ds_read_b128 v[152:155], v0 offset:1024
	ds_read_b128 v[156:159], v0 offset:2048
	ds_read_b128 v[160:163], v0 offset:3072
	v_add_u32_e32 v0, s54, v241
	ds_read_b128 v[132:135], v0
	ds_read_b128 v[136:139], v0 offset:1024
	ds_read_b128 v[140:143], v0 offset:2048
	ds_read_b128 v[144:147], v0 offset:3072
	v_lshl_add_u64 v[2:3], v[218:219], 0, s[34:35]
	s_add_i32 m0, s57, 0xc000
	ds_read_b128 v[176:179], v243
	ds_read_b128 v[192:195], v243 offset:1024
	ds_read_b128 v[172:175], v243 offset:2048
	ds_read_b128 v[188:191], v243 offset:3072
	ds_read_b128 v[168:171], v243 offset:4096
	ds_read_b128 v[184:187], v243 offset:5120
	ds_read_b128 v[164:167], v243 offset:6144
	ds_read_b128 v[180:183], v243 offset:7168
	global_load_lds_dwordx4 v[2:3], off
	v_lshl_add_u64 v[2:3], v[216:217], 0, s[34:35]
	s_add_i32 m0, s57, 0xe000
	s_nop 0
	global_load_lds_dwordx4 v[2:3], off
	s_waitcnt vmcnt(8)
	s_waitcnt lgkmcnt(0)
	s_barrier
	s_setprio 1
	s_waitcnt lgkmcnt(0)
	v_mfma_f32_16x16x32_bf16 v[128:131], v[148:151], v[176:179], v[128:131]
	v_mfma_f32_16x16x32_bf16 v[124:127], v[156:159], v[176:179], v[124:127]
	v_mfma_f32_16x16x32_bf16 v[120:123], v[148:151], v[172:175], v[120:123]
	v_mfma_f32_16x16x32_bf16 v[112:115], v[156:159], v[172:175], v[112:115]
	v_mfma_f32_16x16x32_bf16 v[104:107], v[148:151], v[168:171], v[104:107]
	v_mfma_f32_16x16x32_bf16 v[96:99], v[156:159], v[168:171], v[96:99]
	v_mfma_f32_16x16x32_bf16 v[88:91], v[148:151], v[164:167], v[88:91]
	v_mfma_f32_16x16x32_bf16 v[80:83], v[156:159], v[164:167], v[80:83]
	v_mfma_f32_16x16x32_bf16 v[128:131], v[152:155], v[192:195], v[128:131]
	v_mfma_f32_16x16x32_bf16 v[124:127], v[160:163], v[192:195], v[124:127]
	v_mfma_f32_16x16x32_bf16 v[120:123], v[152:155], v[188:191], v[120:123]
	v_mfma_f32_16x16x32_bf16 v[112:115], v[160:163], v[188:191], v[112:115]
	v_mfma_f32_16x16x32_bf16 v[104:107], v[152:155], v[184:187], v[104:107]
	v_mfma_f32_16x16x32_bf16 v[96:99], v[160:163], v[184:187], v[96:99]
	v_mfma_f32_16x16x32_bf16 v[88:91], v[152:155], v[180:183], v[88:91]
	v_mfma_f32_16x16x32_bf16 v[80:83], v[160:163], v[180:183], v[80:83]
	s_setprio 0
	s_setprio 1
	v_mfma_f32_16x16x32_bf16 v[116:119], v[132:135], v[176:179], v[116:119]
	v_mfma_f32_16x16x32_bf16 v[108:111], v[140:143], v[176:179], v[108:111]
	v_mfma_f32_16x16x32_bf16 v[100:103], v[132:135], v[172:175], v[100:103]
	v_mfma_f32_16x16x32_bf16 v[92:95], v[140:143], v[172:175], v[92:95]
	v_mfma_f32_16x16x32_bf16 v[84:87], v[132:135], v[168:171], v[84:87]
	v_mfma_f32_16x16x32_bf16 v[76:79], v[140:143], v[168:171], v[76:79]
	v_mfma_f32_16x16x32_bf16 v[72:75], v[132:135], v[164:167], v[72:75]
	v_mfma_f32_16x16x32_bf16 v[68:71], v[140:143], v[164:167], v[68:71]
	v_mfma_f32_16x16x32_bf16 v[116:119], v[136:139], v[192:195], v[116:119]
	v_mfma_f32_16x16x32_bf16 v[108:111], v[144:147], v[192:195], v[108:111]
	v_mfma_f32_16x16x32_bf16 v[100:103], v[136:139], v[188:191], v[100:103]
	v_mfma_f32_16x16x32_bf16 v[92:95], v[144:147], v[188:191], v[92:95]
	v_mfma_f32_16x16x32_bf16 v[84:87], v[136:139], v[184:187], v[84:87]
	v_mfma_f32_16x16x32_bf16 v[76:79], v[144:147], v[184:187], v[76:79]
	v_mfma_f32_16x16x32_bf16 v[72:75], v[136:139], v[180:183], v[72:75]
	v_mfma_f32_16x16x32_bf16 v[68:71], v[144:147], v[180:183], v[68:71]
	s_setprio 0
	s_barrier
	v_cndmask_b32_e64 v0, 0, 1, s[36:37]
	v_cmp_ne_u32_e64 s[6:7], 1, v0
	s_andn2_b64 vcc, exec, s[36:37]
	s_cbranch_vccnz .LBB0_775
	ds_read_b128 v[176:179], v243 offset:16384
	ds_read_b128 v[192:195], v243 offset:17408
	ds_read_b128 v[172:175], v243 offset:18432
	ds_read_b128 v[188:191], v243 offset:19456
	ds_read_b128 v[168:171], v243 offset:20480
	ds_read_b128 v[184:187], v243 offset:21504
	ds_read_b128 v[164:167], v243 offset:22528
	ds_read_b128 v[180:183], v243 offset:23552

.LBB0_777:
	s_barrier
	v_add_u32_e32 v0, s61, v241
	ds_read_b128 v[148:151], v0
	ds_read_b128 v[152:155], v0 offset:1024
	ds_read_b128 v[156:159], v0 offset:2048
	ds_read_b128 v[160:163], v0 offset:3072
	v_add_u32_e32 v0, s76, v241
	ds_read_b128 v[132:135], v0
	ds_read_b128 v[136:139], v0 offset:1024
	ds_read_b128 v[140:143], v0 offset:2048
	ds_read_b128 v[144:147], v0 offset:3072
	s_and_b64 s[42:43], s[22:23], s[42:43]
	s_and_b64 s[42:43], s[42:43], exec
	s_cselect_b32 s43, s74, s30
	s_cselect_b32 s42, 0, s31
	s_add_u32 s40, s40, s43
	s_addc_u32 s41, s41, s42
	s_mov_b32 m0, s59
	v_lshl_add_u64 v[244:245], s[40:41], 0, v[202:203]
	ds_read_b128 v[176:179], v243 offset:32768
	ds_read_b128 v[192:195], v243 offset:33792
	ds_read_b128 v[172:175], v243 offset:34816
	ds_read_b128 v[188:191], v243 offset:35840
	ds_read_b128 v[168:171], v243 offset:36864
	ds_read_b128 v[184:187], v243 offset:37888
	ds_read_b128 v[164:167], v243 offset:38912
	ds_read_b128 v[180:183], v243 offset:39936
	global_load_lds_dwordx4 v[244:245], off
	v_lshl_add_u64 v[244:245], s[40:41], 0, v[206:207]
	s_mov_b32 m0, s60
	s_nop 0
	global_load_lds_dwordx4 v[244:245], off
	s_waitcnt vmcnt(8)
	s_waitcnt lgkmcnt(0)
	s_barrier
	s_setprio 1
	s_waitcnt lgkmcnt(0)
	v_mfma_f32_16x16x32_bf16 v[128:131], v[148:151], v[176:179], v[128:131]
	v_mfma_f32_16x16x32_bf16 v[124:127], v[156:159], v[176:179], v[124:127]
	v_mfma_f32_16x16x32_bf16 v[120:123], v[148:151], v[172:175], v[120:123]
	v_mfma_f32_16x16x32_bf16 v[112:115], v[156:159], v[172:175], v[112:115]
	v_mfma_f32_16x16x32_bf16 v[104:107], v[148:151], v[168:171], v[104:107]
	v_mfma_f32_16x16x32_bf16 v[96:99], v[156:159], v[168:171], v[96:99]
	v_mfma_f32_16x16x32_bf16 v[88:91], v[148:151], v[164:167], v[88:91]
	v_mfma_f32_16x16x32_bf16 v[80:83], v[156:159], v[164:167], v[80:83]
	v_mfma_f32_16x16x32_bf16 v[128:131], v[152:155], v[192:195], v[128:131]
	v_mfma_f32_16x16x32_bf16 v[124:127], v[160:163], v[192:195], v[124:127]
	v_mfma_f32_16x16x32_bf16 v[120:123], v[152:155], v[188:191], v[120:123]
	v_mfma_f32_16x16x32_bf16 v[112:115], v[160:163], v[188:191], v[112:115]
	v_mfma_f32_16x16x32_bf16 v[104:107], v[152:155], v[184:187], v[104:107]
	v_mfma_f32_16x16x32_bf16 v[96:99], v[160:163], v[184:187], v[96:99]
	v_mfma_f32_16x16x32_bf16 v[88:91], v[152:155], v[180:183], v[88:91]
	v_mfma_f32_16x16x32_bf16 v[80:83], v[160:163], v[180:183], v[80:83]
	s_setprio 0
	s_setprio 1
	v_mfma_f32_16x16x32_bf16 v[116:119], v[132:135], v[176:179], v[116:119]
	v_mfma_f32_16x16x32_bf16 v[108:111], v[140:143], v[176:179], v[108:111]
	v_mfma_f32_16x16x32_bf16 v[100:103], v[132:135], v[172:175], v[100:103]
	v_mfma_f32_16x16x32_bf16 v[92:95], v[140:143], v[172:175], v[92:95]
	v_mfma_f32_16x16x32_bf16 v[84:87], v[132:135], v[168:171], v[84:87]
	v_mfma_f32_16x16x32_bf16 v[76:79], v[140:143], v[168:171], v[76:79]
	v_mfma_f32_16x16x32_bf16 v[72:75], v[132:135], v[164:167], v[72:75]
	v_mfma_f32_16x16x32_bf16 v[68:71], v[140:143], v[164:167], v[68:71]
	v_mfma_f32_16x16x32_bf16 v[116:119], v[136:139], v[192:195], v[116:119]
	v_mfma_f32_16x16x32_bf16 v[108:111], v[144:147], v[192:195], v[108:111]
	v_mfma_f32_16x16x32_bf16 v[100:103], v[136:139], v[188:191], v[100:103]
	v_mfma_f32_16x16x32_bf16 v[92:95], v[144:147], v[188:191], v[92:95]
	v_mfma_f32_16x16x32_bf16 v[84:87], v[136:139], v[184:187], v[84:87]
	v_mfma_f32_16x16x32_bf16 v[76:79], v[144:147], v[184:187], v[76:79]
	v_mfma_f32_16x16x32_bf16 v[72:75], v[136:139], v[180:183], v[72:75]
	v_mfma_f32_16x16x32_bf16 v[68:71], v[144:147], v[180:183], v[68:71]
	s_setprio 0
	s_barrier
	s_and_b64 vcc, exec, s[6:7]
	s_mov_b64 s[88:89], s[86:87]
	s_cbranch_vccnz .LBB0_779
	ds_read_b128 v[176:179], v243 offset:49152
	ds_read_b128 v[192:195], v243 offset:50176
	ds_read_b128 v[172:175], v243 offset:51200
	ds_read_b128 v[188:191], v243 offset:52224
	ds_read_b128 v[168:171], v243 offset:53248
	ds_read_b128 v[184:187], v243 offset:54272
	ds_read_b128 v[164:167], v243 offset:55296
	ds_read_b128 v[180:183], v243 offset:56320

.LBB0_1609:
	v_add_u32_e32 v0, s23, v225
	ds_read_b128 v[148:151], v0
	ds_read_b128 v[152:155], v0 offset:1024
	ds_read_b128 v[156:159], v0 offset:2048
	ds_read_b128 v[160:163], v0 offset:3072
	v_add_u32_e32 v0, s50, v225
	ds_read_b128 v[132:135], v0
	ds_read_b128 v[136:139], v0 offset:1024
	ds_read_b128 v[140:143], v0 offset:2048
	ds_read_b128 v[144:147], v0 offset:3072
	v_lshl_add_u64 v[2:3], v[216:217], 0, s[28:29]
	s_add_i32 m0, s53, 0xc000
	ds_read_b128 v[176:179], v241
	ds_read_b128 v[192:195], v241 offset:1024
	ds_read_b128 v[172:175], v241 offset:2048
	ds_read_b128 v[188:191], v241 offset:3072
	ds_read_b128 v[168:171], v241 offset:4096
	ds_read_b128 v[184:187], v241 offset:5120
	ds_read_b128 v[164:167], v241 offset:6144
	ds_read_b128 v[180:183], v241 offset:7168
	global_load_lds_dwordx4 v[2:3], off
	v_lshl_add_u64 v[2:3], v[214:215], 0, s[28:29]
	s_add_i32 m0, s53, 0xe000
	s_nop 0
	global_load_lds_dwordx4 v[2:3], off
	s_waitcnt vmcnt(8)
	s_waitcnt lgkmcnt(0)
	s_barrier
	s_setprio 1
	s_waitcnt lgkmcnt(0)
	v_mfma_f32_16x16x32_bf16 v[128:131], v[148:151], v[176:179], v[128:131]
	v_mfma_f32_16x16x32_bf16 v[120:123], v[156:159], v[176:179], v[120:123]
	v_mfma_f32_16x16x32_bf16 v[112:115], v[148:151], v[172:175], v[112:115]
	v_mfma_f32_16x16x32_bf16 v[104:107], v[156:159], v[172:175], v[104:107]
	v_mfma_f32_16x16x32_bf16 v[96:99], v[148:151], v[168:171], v[96:99]
	v_mfma_f32_16x16x32_bf16 v[88:91], v[156:159], v[168:171], v[88:91]
	v_mfma_f32_16x16x32_bf16 v[80:83], v[148:151], v[164:167], v[80:83]
	v_mfma_f32_16x16x32_bf16 v[72:75], v[156:159], v[164:167], v[72:75]
	v_mfma_f32_16x16x32_bf16 v[128:131], v[152:155], v[192:195], v[128:131]
	v_mfma_f32_16x16x32_bf16 v[120:123], v[160:163], v[192:195], v[120:123]
	v_mfma_f32_16x16x32_bf16 v[112:115], v[152:155], v[188:191], v[112:115]
	v_mfma_f32_16x16x32_bf16 v[104:107], v[160:163], v[188:191], v[104:107]
	v_mfma_f32_16x16x32_bf16 v[96:99], v[152:155], v[184:187], v[96:99]
	v_mfma_f32_16x16x32_bf16 v[88:91], v[160:163], v[184:187], v[88:91]
	v_mfma_f32_16x16x32_bf16 v[80:83], v[152:155], v[180:183], v[80:83]
	v_mfma_f32_16x16x32_bf16 v[72:75], v[160:163], v[180:183], v[72:75]
	s_setprio 0
	s_setprio 1
	v_mfma_f32_16x16x32_bf16 v[124:127], v[132:135], v[176:179], v[124:127]
	v_mfma_f32_16x16x32_bf16 v[116:119], v[140:143], v[176:179], v[116:119]
	v_mfma_f32_16x16x32_bf16 v[108:111], v[132:135], v[172:175], v[108:111]
	v_mfma_f32_16x16x32_bf16 v[100:103], v[140:143], v[172:175], v[100:103]
	v_mfma_f32_16x16x32_bf16 v[92:95], v[132:135], v[168:171], v[92:95]
	v_mfma_f32_16x16x32_bf16 v[84:87], v[140:143], v[168:171], v[84:87]
	v_mfma_f32_16x16x32_bf16 v[76:79], v[132:135], v[164:167], v[76:79]
	v_mfma_f32_16x16x32_bf16 v[68:71], v[140:143], v[164:167], v[68:71]
	v_mfma_f32_16x16x32_bf16 v[124:127], v[136:139], v[192:195], v[124:127]
	v_mfma_f32_16x16x32_bf16 v[116:119], v[144:147], v[192:195], v[116:119]
	v_mfma_f32_16x16x32_bf16 v[108:111], v[136:139], v[188:191], v[108:111]
	v_mfma_f32_16x16x32_bf16 v[100:103], v[144:147], v[188:191], v[100:103]
	v_mfma_f32_16x16x32_bf16 v[92:95], v[136:139], v[184:187], v[92:95]
	v_mfma_f32_16x16x32_bf16 v[84:87], v[144:147], v[184:187], v[84:87]
	v_mfma_f32_16x16x32_bf16 v[76:79], v[136:139], v[180:183], v[76:79]
	v_mfma_f32_16x16x32_bf16 v[68:71], v[144:147], v[180:183], v[68:71]
	s_setprio 0
	s_barrier
	v_cndmask_b32_e64 v0, 0, 1, s[30:31]
	v_cmp_ne_u32_e64 s[4:5], 1, v0
	s_andn2_b64 vcc, exec, s[30:31]
	s_cbranch_vccnz .LBB0_1611
	ds_read_b128 v[176:179], v241 offset:16384
	ds_read_b128 v[192:195], v241 offset:17408
	ds_read_b128 v[172:175], v241 offset:18432
	ds_read_b128 v[188:191], v241 offset:19456
	ds_read_b128 v[168:171], v241 offset:20480
	ds_read_b128 v[184:187], v241 offset:21504
	ds_read_b128 v[164:167], v241 offset:22528
	ds_read_b128 v[180:183], v241 offset:23552

.LBB0_1613:
	s_barrier
	v_add_u32_e32 v0, s57, v225
	ds_read_b128 v[148:151], v0
	ds_read_b128 v[152:155], v0 offset:1024
	ds_read_b128 v[156:159], v0 offset:2048
	ds_read_b128 v[160:163], v0 offset:3072
	v_add_u32_e32 v0, s66, v225
	ds_read_b128 v[132:135], v0
	ds_read_b128 v[136:139], v0 offset:1024
	ds_read_b128 v[140:143], v0 offset:2048
	ds_read_b128 v[144:147], v0 offset:3072
	s_and_b64 s[38:39], s[16:17], s[38:39]
	s_and_b64 s[38:39], s[38:39], exec
	s_cselect_b32 s39, s74, s26
	s_cselect_b32 s38, 0, s27
	s_add_u32 s36, s36, s39
	s_addc_u32 s37, s37, s38
	s_mov_b32 m0, s55
	v_lshl_add_u64 v[242:243], s[36:37], 0, v[202:203]
	ds_read_b128 v[176:179], v241 offset:32768
	ds_read_b128 v[192:195], v241 offset:33792
	ds_read_b128 v[172:175], v241 offset:34816
	ds_read_b128 v[188:191], v241 offset:35840
	ds_read_b128 v[168:171], v241 offset:36864
	ds_read_b128 v[184:187], v241 offset:37888
	ds_read_b128 v[164:167], v241 offset:38912
	ds_read_b128 v[180:183], v241 offset:39936
	global_load_lds_dwordx4 v[242:243], off
	v_lshl_add_u64 v[242:243], s[36:37], 0, v[206:207]
	s_mov_b32 m0, s56
	s_nop 0
	global_load_lds_dwordx4 v[242:243], off
	s_waitcnt vmcnt(8)
	s_waitcnt lgkmcnt(0)
	s_barrier
	s_setprio 1
	s_waitcnt lgkmcnt(0)
	v_mfma_f32_16x16x32_bf16 v[128:131], v[148:151], v[176:179], v[128:131]
	v_mfma_f32_16x16x32_bf16 v[120:123], v[156:159], v[176:179], v[120:123]
	v_mfma_f32_16x16x32_bf16 v[112:115], v[148:151], v[172:175], v[112:115]
	v_mfma_f32_16x16x32_bf16 v[104:107], v[156:159], v[172:175], v[104:107]
	v_mfma_f32_16x16x32_bf16 v[96:99], v[148:151], v[168:171], v[96:99]
	v_mfma_f32_16x16x32_bf16 v[88:91], v[156:159], v[168:171], v[88:91]
	v_mfma_f32_16x16x32_bf16 v[80:83], v[148:151], v[164:167], v[80:83]
	v_mfma_f32_16x16x32_bf16 v[72:75], v[156:159], v[164:167], v[72:75]
	v_mfma_f32_16x16x32_bf16 v[128:131], v[152:155], v[192:195], v[128:131]
	v_mfma_f32_16x16x32_bf16 v[120:123], v[160:163], v[192:195], v[120:123]
	v_mfma_f32_16x16x32_bf16 v[112:115], v[152:155], v[188:191], v[112:115]
	v_mfma_f32_16x16x32_bf16 v[104:107], v[160:163], v[188:191], v[104:107]
	v_mfma_f32_16x16x32_bf16 v[96:99], v[152:155], v[184:187], v[96:99]
	v_mfma_f32_16x16x32_bf16 v[88:91], v[160:163], v[184:187], v[88:91]
	v_mfma_f32_16x16x32_bf16 v[80:83], v[152:155], v[180:183], v[80:83]
	v_mfma_f32_16x16x32_bf16 v[72:75], v[160:163], v[180:183], v[72:75]
	s_setprio 0
	s_setprio 1
	v_mfma_f32_16x16x32_bf16 v[124:127], v[132:135], v[176:179], v[124:127]
	v_mfma_f32_16x16x32_bf16 v[116:119], v[140:143], v[176:179], v[116:119]
	v_mfma_f32_16x16x32_bf16 v[108:111], v[132:135], v[172:175], v[108:111]
	v_mfma_f32_16x16x32_bf16 v[100:103], v[140:143], v[172:175], v[100:103]
	v_mfma_f32_16x16x32_bf16 v[92:95], v[132:135], v[168:171], v[92:95]
	v_mfma_f32_16x16x32_bf16 v[84:87], v[140:143], v[168:171], v[84:87]
	v_mfma_f32_16x16x32_bf16 v[76:79], v[132:135], v[164:167], v[76:79]
	v_mfma_f32_16x16x32_bf16 v[68:71], v[140:143], v[164:167], v[68:71]
	v_mfma_f32_16x16x32_bf16 v[124:127], v[136:139], v[192:195], v[124:127]
	v_mfma_f32_16x16x32_bf16 v[116:119], v[144:147], v[192:195], v[116:119]
	v_mfma_f32_16x16x32_bf16 v[108:111], v[136:139], v[188:191], v[108:111]
	v_mfma_f32_16x16x32_bf16 v[100:103], v[144:147], v[188:191], v[100:103]
	v_mfma_f32_16x16x32_bf16 v[92:95], v[136:139], v[184:187], v[92:95]
	v_mfma_f32_16x16x32_bf16 v[84:87], v[144:147], v[184:187], v[84:87]
	v_mfma_f32_16x16x32_bf16 v[76:79], v[136:139], v[180:183], v[76:79]
	v_mfma_f32_16x16x32_bf16 v[68:71], v[144:147], v[180:183], v[68:71]
	s_setprio 0
	s_barrier
	s_and_b64 vcc, exec, s[4:5]
	s_mov_b64 s[88:89], s[86:87]
	s_cbranch_vccnz .LBB0_1615
	ds_read_b128 v[176:179], v241 offset:49152
	ds_read_b128 v[192:195], v241 offset:50176
	ds_read_b128 v[172:175], v241 offset:51200
	ds_read_b128 v[188:191], v241 offset:52224
	ds_read_b128 v[168:171], v241 offset:53248
	ds_read_b128 v[184:187], v241 offset:54272
	ds_read_b128 v[164:167], v241 offset:55296
	ds_read_b128 v[180:183], v241 offset:56320
